# v17 + SB vote flags via DS ops + deferred K-loop MFMAs overlapped with rstab row-sum loads
# speedup vs baseline: 1.0097x; 1.0097x over previous
.Lgk_even_mid:
	s_cmp_lt_u32 s28, s47
	s_cselect_b64 s[30:31], -1, 0
	s_cmp_ge_u32 s28, s47
	s_cselect_b64 s[6:7], -1, 0
	s_or_b64 s[36:37], s[26:27], s[30:31]
	s_and_b64 s[30:31], s[30:31], exec
	s_cselect_b32 s30, s1, s5
	s_cselect_b32 s29, s15, 0
	s_cselect_b32 s67, s43, s93
	s_cselect_b32 s66, s42, s92
	s_cselect_b32 s65, s41, s57
	s_cselect_b32 s64, s40, s56
	s_cselect_b32 s71, s63, s91
	s_cselect_b32 s70, s62, s90
	s_cselect_b32 s69, s61, s53
	s_cselect_b32 s68, s60, s52
	s_add_i32 s30, s29, s30
	s_and_b32 s66, s66, s36
	s_and_b32 s70, s70, s36
	v_mfma_f32_16x16x32_bf16 v[126:129], v[130:133], v[146:149], v[126:129]
	ds_read_b128 v[178:181], v241 offset:32768
	v_mfma_f32_16x16x32_bf16 v[122:125], v[134:137], v[146:149], v[122:125]
	v_mfma_f32_16x16x32_bf16 v[118:121], v[138:141], v[146:149], v[118:121]
	ds_read_b128 v[182:185], v241 offset:34816
	v_mfma_f32_16x16x32_bf16 v[114:117], v[142:145], v[146:149], v[114:117]
	v_mfma_f32_16x16x32_bf16 v[110:113], v[130:133], v[150:153], v[110:113]
	ds_read_b128 v[186:189], v241 offset:36864
	v_mfma_f32_16x16x32_bf16 v[106:109], v[134:137], v[150:153], v[106:109]
	v_mfma_f32_16x16x32_bf16 v[102:105], v[138:141], v[150:153], v[102:105]
	ds_read_b128 v[190:193], v241 offset:38912
	v_mfma_f32_16x16x32_bf16 v[98:101], v[142:145], v[150:153], v[98:101]
	v_mfma_f32_16x16x32_bf16 v[94:97], v[130:133], v[154:157], v[94:97]
	ds_read_b128 v[194:197], v233
	v_mfma_f32_16x16x32_bf16 v[90:93], v[134:137], v[154:157], v[90:93]
	v_mfma_f32_16x16x32_bf16 v[86:89], v[138:141], v[154:157], v[86:89]
	ds_read_b128 v[198:201], v233 offset:2048
	v_mfma_f32_16x16x32_bf16 v[82:85], v[142:145], v[154:157], v[82:85]
	v_mfma_f32_16x16x32_bf16 v[78:81], v[130:133], v[158:161], v[78:81]
	ds_read_b128 v[202:205], v233 offset:4096
	v_mfma_f32_16x16x32_bf16 v[74:77], v[134:137], v[158:161], v[74:77]
	v_mfma_f32_16x16x32_bf16 v[70:73], v[138:141], v[158:161], v[70:73]
	ds_read_b128 v[206:209], v233 offset:6144
	v_mfma_f32_16x16x32_bf16 v[66:69], v[142:145], v[158:161], v[66:69]
	v_mfma_f32_16x16x32_bf16 v[62:65], v[130:133], v[162:165], v[62:65]
	ds_read_b128 v[210:213], v233 offset:8192
	v_mfma_f32_16x16x32_bf16 v[58:61], v[134:137], v[162:165], v[58:61]
	v_mfma_f32_16x16x32_bf16 v[54:57], v[138:141], v[162:165], v[54:57]
	ds_read_b128 v[214:217], v233 offset:10240
	v_mfma_f32_16x16x32_bf16 v[50:53], v[142:145], v[162:165], v[50:53]
	v_mfma_f32_16x16x32_bf16 v[46:49], v[130:133], v[166:169], v[46:49]
	ds_read_b128 v[218:221], v233 offset:12288
	v_mfma_f32_16x16x32_bf16 v[42:45], v[134:137], v[166:169], v[42:45]
	v_mfma_f32_16x16x32_bf16 v[38:41], v[138:141], v[166:169], v[38:41]
	ds_read_b128 v[222:225], v233 offset:14336
	v_mfma_f32_16x16x32_bf16 v[34:37], v[142:145], v[166:169], v[34:37]
	v_mfma_f32_16x16x32_bf16 v[30:33], v[130:133], v[170:173], v[30:33]
	v_mfma_f32_16x16x32_bf16 v[26:29], v[134:137], v[170:173], v[26:29]
	v_mfma_f32_16x16x32_bf16 v[22:25], v[138:141], v[170:173], v[22:25]
	v_mfma_f32_16x16x32_bf16 v[18:21], v[142:145], v[170:173], v[18:21]
	v_mfma_f32_16x16x32_bf16 v[14:17], v[130:133], v[174:177], v[14:17]
	v_mfma_f32_16x16x32_bf16 v[10:13], v[134:137], v[174:177], v[10:13]
	v_mfma_f32_16x16x32_bf16 v[6:9], v[138:141], v[174:177], v[6:9]
	v_mfma_f32_16x16x32_bf16 v[2:5], v[142:145], v[174:177], v[2:5]
	s_waitcnt vmcnt(0) lgkmcnt(0)
	s_barrier
	v_mfma_f32_16x16x32_bf16 v[126:129], v[178:181], v[194:197], v[126:129]
	ds_read_b128 v[130:133], v226 offset:32768
	v_mfma_f32_16x16x32_bf16 v[122:125], v[182:185], v[194:197], v[122:125]
	s_mov_b32 m0, s76
	s_add_i32 s39, s29, s96
	buffer_load_dwordx4 v227, s[64:67], s39 offen lds
	v_mfma_f32_16x16x32_bf16 v[118:121], v[186:189], v[194:197], v[118:121]
	ds_read_b128 v[134:137], v226 offset:34816
	v_mfma_f32_16x16x32_bf16 v[114:117], v[190:193], v[194:197], v[114:117]
	v_mfma_f32_16x16x32_bf16 v[110:113], v[178:181], v[198:201], v[110:113]
	ds_read_b128 v[138:141], v226 offset:36864
	v_mfma_f32_16x16x32_bf16 v[106:109], v[182:185], v[198:201], v[106:109]
	s_mov_b32 m0, s97
	s_nop 0
	buffer_load_dwordx4 v227, s[68:71], s30 offen lds
	v_mfma_f32_16x16x32_bf16 v[102:105], v[186:189], v[198:201], v[102:105]
	ds_read_b128 v[142:145], v226 offset:38912
	v_mfma_f32_16x16x32_bf16 v[98:101], v[190:193], v[198:201], v[98:101]
	v_mfma_f32_16x16x32_bf16 v[94:97], v[178:181], v[202:205], v[94:97]
	ds_read_b128 v[146:149], v235
	v_mfma_f32_16x16x32_bf16 v[90:93], v[182:185], v[202:205], v[90:93]
	s_mov_b32 m0, s94
	s_add_i32 s39, s29, s12
	buffer_load_dwordx4 v229, s[64:67], s39 offen lds
	v_mfma_f32_16x16x32_bf16 v[86:89], v[186:189], v[202:205], v[86:89]
	ds_read_b128 v[150:153], v235 offset:2048
	v_mfma_f32_16x16x32_bf16 v[82:85], v[190:193], v[202:205], v[82:85]
	v_mfma_f32_16x16x32_bf16 v[78:81], v[178:181], v[206:209], v[78:81]
	ds_read_b128 v[154:157], v235 offset:4096
	v_mfma_f32_16x16x32_bf16 v[74:77], v[182:185], v[206:209], v[74:77]
	s_mov_b32 m0, s95
	s_add_i32 s39, s30, s16
	buffer_load_dwordx4 v229, s[68:71], s39 offen lds
	v_mfma_f32_16x16x32_bf16 v[70:73], v[186:189], v[206:209], v[70:73]
	ds_read_b128 v[158:161], v235 offset:6144
	v_mfma_f32_16x16x32_bf16 v[66:69], v[190:193], v[206:209], v[66:69]
	v_mfma_f32_16x16x32_bf16 v[62:65], v[178:181], v[210:213], v[62:65]
	ds_read_b128 v[162:165], v235 offset:8192
	v_mfma_f32_16x16x32_bf16 v[58:61], v[182:185], v[210:213], v[58:61]
	s_mov_b32 m0, s87
	s_add_i32 s39, s29, s86
	buffer_load_dwordx4 v227, s[64:67], s39 offen lds
	v_mfma_f32_16x16x32_bf16 v[54:57], v[186:189], v[210:213], v[54:57]
	ds_read_b128 v[166:169], v235 offset:10240
	v_mfma_f32_16x16x32_bf16 v[50:53], v[190:193], v[210:213], v[50:53]
	v_mfma_f32_16x16x32_bf16 v[46:49], v[178:181], v[214:217], v[46:49]
	ds_read_b128 v[170:173], v235 offset:12288
	v_mfma_f32_16x16x32_bf16 v[42:45], v[182:185], v[214:217], v[42:45]
	s_mov_b32 m0, s20
	s_add_i32 s39, s30, s10
	buffer_load_dwordx4 v227, s[68:71], s39 offen lds
	v_mfma_f32_16x16x32_bf16 v[38:41], v[186:189], v[214:217], v[38:41]
	ds_read_b128 v[174:177], v235 offset:14336
	v_mfma_f32_16x16x32_bf16 v[34:37], v[190:193], v[214:217], v[34:37]
	v_mfma_f32_16x16x32_bf16 v[30:33], v[178:181], v[218:221], v[30:33]
	v_mfma_f32_16x16x32_bf16 v[26:29], v[182:185], v[218:221], v[26:29]
	s_mov_b32 m0, s22
	s_add_i32 s39, s29, s21
	buffer_load_dwordx4 v229, s[64:67], s39 offen lds
	v_mfma_f32_16x16x32_bf16 v[22:25], v[186:189], v[218:221], v[22:25]
	v_mfma_f32_16x16x32_bf16 v[18:21], v[190:193], v[218:221], v[18:21]
	v_mfma_f32_16x16x32_bf16 v[14:17], v[178:181], v[222:225], v[14:17]
	v_mfma_f32_16x16x32_bf16 v[10:13], v[182:185], v[222:225], v[10:13]
	s_mov_b32 m0, s23
	s_add_i32 s37, s30, s10
	s_add_i32 s39, s37, s16
	buffer_load_dwordx4 v229, s[68:71], s39 offen lds
	v_mfma_f32_16x16x32_bf16 v[6:9], v[186:189], v[222:225], v[6:9]
	v_mfma_f32_16x16x32_bf16 v[2:5], v[190:193], v[222:225], v[2:5]
	s_waitcnt lgkmcnt(0)
	v_mfma_f32_16x16x32_bf16 v[126:129], v[130:133], v[146:149], v[126:129]
	ds_read_b128 v[178:181], v228 offset:32768
	v_mfma_f32_16x16x32_bf16 v[122:125], v[134:137], v[146:149], v[122:125]
	v_mfma_f32_16x16x32_bf16 v[118:121], v[138:141], v[146:149], v[118:121]
	ds_read_b128 v[182:185], v228 offset:34816
	v_mfma_f32_16x16x32_bf16 v[114:117], v[142:145], v[146:149], v[114:117]
	v_mfma_f32_16x16x32_bf16 v[110:113], v[130:133], v[150:153], v[110:113]
	ds_read_b128 v[186:189], v228 offset:36864
	v_mfma_f32_16x16x32_bf16 v[106:109], v[134:137], v[150:153], v[106:109]
	v_mfma_f32_16x16x32_bf16 v[102:105], v[138:141], v[150:153], v[102:105]
	ds_read_b128 v[190:193], v228 offset:38912
	v_mfma_f32_16x16x32_bf16 v[98:101], v[142:145], v[150:153], v[98:101]
	v_mfma_f32_16x16x32_bf16 v[94:97], v[130:133], v[154:157], v[94:97]
	ds_read_b128 v[194:197], v237
	v_mfma_f32_16x16x32_bf16 v[90:93], v[134:137], v[154:157], v[90:93]
	v_mfma_f32_16x16x32_bf16 v[86:89], v[138:141], v[154:157], v[86:89]
	ds_read_b128 v[198:201], v237 offset:2048
	v_mfma_f32_16x16x32_bf16 v[82:85], v[142:145], v[154:157], v[82:85]
	v_mfma_f32_16x16x32_bf16 v[78:81], v[130:133], v[158:161], v[78:81]
	ds_read_b128 v[202:205], v237 offset:4096
	v_mfma_f32_16x16x32_bf16 v[74:77], v[134:137], v[158:161], v[74:77]
	v_mfma_f32_16x16x32_bf16 v[70:73], v[138:141], v[158:161], v[70:73]
	ds_read_b128 v[206:209], v237 offset:6144
	v_mfma_f32_16x16x32_bf16 v[66:69], v[142:145], v[158:161], v[66:69]
	v_mfma_f32_16x16x32_bf16 v[62:65], v[130:133], v[162:165], v[62:65]
	ds_read_b128 v[210:213], v237 offset:8192
	v_mfma_f32_16x16x32_bf16 v[58:61], v[134:137], v[162:165], v[58:61]
	v_mfma_f32_16x16x32_bf16 v[54:57], v[138:141], v[162:165], v[54:57]
	ds_read_b128 v[214:217], v237 offset:10240
	v_mfma_f32_16x16x32_bf16 v[50:53], v[142:145], v[162:165], v[50:53]
	v_mfma_f32_16x16x32_bf16 v[46:49], v[130:133], v[166:169], v[46:49]
	ds_read_b128 v[218:221], v237 offset:12288
	v_mfma_f32_16x16x32_bf16 v[42:45], v[134:137], v[166:169], v[42:45]
	v_mfma_f32_16x16x32_bf16 v[38:41], v[138:141], v[166:169], v[38:41]
	ds_read_b128 v[222:225], v237 offset:14336
	v_mfma_f32_16x16x32_bf16 v[34:37], v[142:145], v[166:169], v[34:37]
	v_mfma_f32_16x16x32_bf16 v[30:33], v[130:133], v[170:173], v[30:33]
	v_mfma_f32_16x16x32_bf16 v[26:29], v[134:137], v[170:173], v[26:29]
	v_mfma_f32_16x16x32_bf16 v[22:25], v[138:141], v[170:173], v[22:25]
	v_mfma_f32_16x16x32_bf16 v[18:21], v[142:145], v[170:173], v[18:21]
	v_mfma_f32_16x16x32_bf16 v[14:17], v[130:133], v[174:177], v[14:17]
	v_mfma_f32_16x16x32_bf16 v[10:13], v[134:137], v[174:177], v[10:13]
	v_mfma_f32_16x16x32_bf16 v[6:9], v[138:141], v[174:177], v[6:9]
	v_mfma_f32_16x16x32_bf16 v[2:5], v[142:145], v[174:177], v[2:5]
	s_addk_i32 s15, 0x100
	s_add_i32 s28, s28, 2
	s_and_b64 vcc, exec, s[6:7]
	s_waitcnt vmcnt(0) lgkmcnt(0)
	s_barrier
	s_cbranch_vccz .Lgk_even_top
	v_mov_b32_e32 v226, 0x8000
	v_mov_b32_e32 v228, 0x8004

.Lgk_rs_mf:
	s_or_b64 exec, exec, s[6:7]
	s_nop 3
	v_mfma_f32_16x16x32_bf16 v[126:129], v[178:181], v[194:197], v[126:129]
	v_mfma_f32_16x16x32_bf16 v[122:125], v[182:185], v[194:197], v[122:125]
	v_mfma_f32_16x16x32_bf16 v[118:121], v[186:189], v[194:197], v[118:121]
	v_mfma_f32_16x16x32_bf16 v[114:117], v[190:193], v[194:197], v[114:117]
	v_mfma_f32_16x16x32_bf16 v[110:113], v[178:181], v[198:201], v[110:113]
	v_mfma_f32_16x16x32_bf16 v[106:109], v[182:185], v[198:201], v[106:109]
	v_mfma_f32_16x16x32_bf16 v[102:105], v[186:189], v[198:201], v[102:105]
	v_mfma_f32_16x16x32_bf16 v[98:101], v[190:193], v[198:201], v[98:101]
	v_mfma_f32_16x16x32_bf16 v[94:97], v[178:181], v[202:205], v[94:97]
	v_mfma_f32_16x16x32_bf16 v[90:93], v[182:185], v[202:205], v[90:93]
	v_mfma_f32_16x16x32_bf16 v[86:89], v[186:189], v[202:205], v[86:89]
	v_mfma_f32_16x16x32_bf16 v[82:85], v[190:193], v[202:205], v[82:85]
	v_mfma_f32_16x16x32_bf16 v[78:81], v[178:181], v[206:209], v[78:81]
	v_mfma_f32_16x16x32_bf16 v[74:77], v[182:185], v[206:209], v[74:77]
	v_mfma_f32_16x16x32_bf16 v[70:73], v[186:189], v[206:209], v[70:73]
	v_mfma_f32_16x16x32_bf16 v[66:69], v[190:193], v[206:209], v[66:69]
	v_mfma_f32_16x16x32_bf16 v[62:65], v[178:181], v[210:213], v[62:65]
	v_mfma_f32_16x16x32_bf16 v[58:61], v[182:185], v[210:213], v[58:61]
	v_mfma_f32_16x16x32_bf16 v[54:57], v[186:189], v[210:213], v[54:57]
	v_mfma_f32_16x16x32_bf16 v[50:53], v[190:193], v[210:213], v[50:53]
	v_mfma_f32_16x16x32_bf16 v[46:49], v[178:181], v[214:217], v[46:49]
	v_mfma_f32_16x16x32_bf16 v[42:45], v[182:185], v[214:217], v[42:45]
	v_mfma_f32_16x16x32_bf16 v[38:41], v[186:189], v[214:217], v[38:41]
	v_mfma_f32_16x16x32_bf16 v[34:37], v[190:193], v[214:217], v[34:37]
	v_mfma_f32_16x16x32_bf16 v[30:33], v[178:181], v[218:221], v[30:33]
	v_mfma_f32_16x16x32_bf16 v[26:29], v[182:185], v[218:221], v[26:29]
	v_mfma_f32_16x16x32_bf16 v[22:25], v[186:189], v[218:221], v[22:25]
	v_mfma_f32_16x16x32_bf16 v[18:21], v[190:193], v[218:221], v[18:21]
	v_mfma_f32_16x16x32_bf16 v[14:17], v[178:181], v[222:225], v[14:17]
	v_mfma_f32_16x16x32_bf16 v[10:13], v[182:185], v[222:225], v[10:13]
	v_mfma_f32_16x16x32_bf16 v[6:9], v[186:189], v[222:225], v[6:9]
	v_mfma_f32_16x16x32_bf16 v[2:5], v[190:193], v[222:225], v[2:5]
	s_and_saveexec_b64 s[6:7], vcc
	s_cbranch_execz .LBB0_298
	s_waitcnt vmcnt(2)
	v_pk_add_f32 v[132:133], v[132:133], v[136:137]
	v_pk_add_f32 v[130:131], v[130:131], v[134:135]
	s_waitcnt vmcnt(0)
	v_pk_add_f32 v[134:135], v[140:141], v[144:145]
	v_pk_add_f32 v[136:137], v[138:139], v[142:143]
	v_pk_add_f32 v[132:133], v[132:133], v[134:135]
	v_pk_add_f32 v[130:131], v[130:131], v[136:137]
	s_nop 0
	v_pk_mov_b32 v[134:135], v[130:131], v[132:133] op_sel:[1,0]
	v_mov_b32_e32 v131, v133
	v_pk_add_f32 v[130:131], v[134:135], v[130:131]
	s_nop 0
	v_add_f32_e32 v130, v130, v131
	v_fmamk_f32 v130, v130, 0x3a800000, v244
	v_mul_f32_e32 v131, 0x4b800000, v130
	v_cmp_gt_f32_e32 vcc, s33, v130
	s_nop 1
	v_cndmask_b32_e32 v130, v130, v131, vcc
	v_rsq_f32_e32 v130, v130
	s_nop 0
	v_mul_f32_e32 v131, 0x45800000, v130
	v_cndmask_b32_e32 v130, v130, v131, vcc
	v_mov_b32_e32 v131, 0x20000
	v_lshl_add_u32 v0, v0, 2, v131
	ds_write_b32 v0, v130
.LBB0_298:
	s_or_b64 exec, exec, s[6:7]
	s_waitcnt lgkmcnt(0)
	s_barrier
	s_branch .LBB0_299
.Lgk_nors:
	v_mfma_f32_16x16x32_bf16 v[126:129], v[178:181], v[194:197], v[126:129]
	v_mfma_f32_16x16x32_bf16 v[122:125], v[182:185], v[194:197], v[122:125]
	v_mfma_f32_16x16x32_bf16 v[118:121], v[186:189], v[194:197], v[118:121]
	v_mfma_f32_16x16x32_bf16 v[114:117], v[190:193], v[194:197], v[114:117]
	v_mfma_f32_16x16x32_bf16 v[110:113], v[178:181], v[198:201], v[110:113]
	v_mfma_f32_16x16x32_bf16 v[106:109], v[182:185], v[198:201], v[106:109]
	v_mfma_f32_16x16x32_bf16 v[102:105], v[186:189], v[198:201], v[102:105]
	v_mfma_f32_16x16x32_bf16 v[98:101], v[190:193], v[198:201], v[98:101]
	v_mfma_f32_16x16x32_bf16 v[94:97], v[178:181], v[202:205], v[94:97]
	v_mfma_f32_16x16x32_bf16 v[90:93], v[182:185], v[202:205], v[90:93]
	v_mfma_f32_16x16x32_bf16 v[86:89], v[186:189], v[202:205], v[86:89]
	v_mfma_f32_16x16x32_bf16 v[82:85], v[190:193], v[202:205], v[82:85]
	v_mfma_f32_16x16x32_bf16 v[78:81], v[178:181], v[206:209], v[78:81]
	v_mfma_f32_16x16x32_bf16 v[74:77], v[182:185], v[206:209], v[74:77]
	v_mfma_f32_16x16x32_bf16 v[70:73], v[186:189], v[206:209], v[70:73]
	v_mfma_f32_16x16x32_bf16 v[66:69], v[190:193], v[206:209], v[66:69]
	v_mfma_f32_16x16x32_bf16 v[62:65], v[178:181], v[210:213], v[62:65]
	v_mfma_f32_16x16x32_bf16 v[58:61], v[182:185], v[210:213], v[58:61]
	v_mfma_f32_16x16x32_bf16 v[54:57], v[186:189], v[210:213], v[54:57]
	v_mfma_f32_16x16x32_bf16 v[50:53], v[190:193], v[210:213], v[50:53]
	v_mfma_f32_16x16x32_bf16 v[46:49], v[178:181], v[214:217], v[46:49]
	v_mfma_f32_16x16x32_bf16 v[42:45], v[182:185], v[214:217], v[42:45]
	v_mfma_f32_16x16x32_bf16 v[38:41], v[186:189], v[214:217], v[38:41]
	v_mfma_f32_16x16x32_bf16 v[34:37], v[190:193], v[214:217], v[34:37]
	v_mfma_f32_16x16x32_bf16 v[30:33], v[178:181], v[218:221], v[30:33]
	v_mfma_f32_16x16x32_bf16 v[26:29], v[182:185], v[218:221], v[26:29]
	v_mfma_f32_16x16x32_bf16 v[22:25], v[186:189], v[218:221], v[22:25]
	v_mfma_f32_16x16x32_bf16 v[18:21], v[190:193], v[218:221], v[18:21]
	v_mfma_f32_16x16x32_bf16 v[14:17], v[178:181], v[222:225], v[14:17]
	v_mfma_f32_16x16x32_bf16 v[10:13], v[182:185], v[222:225], v[10:13]
	v_mfma_f32_16x16x32_bf16 v[6:9], v[186:189], v[222:225], v[6:9]
	v_mfma_f32_16x16x32_bf16 v[2:5], v[190:193], v[222:225], v[2:5]
	s_nop 7
	s_nop 7
